# speedup vs baseline: 1.0079x; 1.0074x over previous
; template <bool MLA>
; __device__ __forceinline__ void attn_item(unsigned char* smem, const Params& p, int b, int hh, int qt) {
;     ...
;     lsum += __shfl_xor(lsum, 32);
;     const float inv = 1.0f / lsum;
; #pragma unroll
;     for (int d = 0; d < 4; ++d)
; #pragma unroll
;         for (int t = 0; t < 4; ++t) {
;             uint2 ov;
;             ov.x = pack2(o[d][4 * t] * inv, o[d][4 * t + 1] * inv);
;             ov.y = pack2(o[d][4 * t + 2] * inv, o[d][4 * t + 3] * inv);
;             *(uint2*)(obase + d * 32 + 8 * t + 4 * h5) = ov;
;         }
.LBB0_830:
	v_sub_f32_e32 v70, v77, v198
	v_exp_f32_e32 v106, v70
	v_sub_f32_e32 v70, v76, v198
	v_exp_f32_e32 v107, v70
	v_sub_f32_e32 v70, v75, v198
	v_sub_f32_e32 v66, v66, v198
	v_exp_f32_e32 v108, v70
	v_sub_f32_e32 v70, v74, v198
	v_sub_f32_e32 v69, v69, v198
	v_sub_f32_e32 v68, v68, v198
	v_sub_f32_e32 v67, v67, v198
	v_exp_f32_e32 v113, v66
	v_sub_f32_e32 v66, 0xff800000, v198
	v_exp_f32_e32 v109, v70
	v_exp_f32_e32 v110, v69
	v_exp_f32_e32 v111, v68
	v_exp_f32_e32 v112, v67
	v_exp_f32_e32 v114, v66
	ds_read_b128 v[70:73], v98 offset:12288
	ds_read_b128 v[74:77], v98 offset:8192
	ds_read_b128 v[78:81], v0 offset:12288
	ds_read_b128 v[98:101], v0 offset:8192
	v_cvt_pk_bf16_f32 v66, v114, v114
	v_mov_b32_e32 v67, v66
	v_mov_b32_e32 v68, v66
	v_mov_b32_e32 v69, v66
	v_cvt_pk_bf16_f32 v102, v106, v107
	v_cvt_pk_bf16_f32 v103, v108, v109
	v_cvt_pk_bf16_f32 v104, v110, v111
	v_cvt_pk_bf16_f32 v105, v112, v113
	s_setprio 1
	s_nop 0
	v_mfma_f32_32x32x16_bf16 v[50:65], v[90:93], v[102:105], v[50:65]
	v_mfma_f32_32x32x16_bf16 v[34:49], v[82:85], v[102:105], v[34:49]
	s_waitcnt lgkmcnt(0)
	v_mfma_f32_32x32x16_bf16 v[18:33], v[98:101], v[102:105], v[18:33]
	v_mfma_f32_32x32x16_bf16 v[2:17], v[78:81], v[102:105], v[2:17]
	v_mfma_f32_32x32x16_bf16 v[50:65], v[94:97], v[66:69], v[50:65]
	v_mfma_f32_32x32x16_bf16 v[34:49], v[86:89], v[66:69], v[34:49]
	v_mfma_f32_32x32x16_bf16 v[18:33], v[74:77], v[66:69], v[18:33]
	v_mfma_f32_32x32x16_bf16 v[2:17], v[70:73], v[66:69], v[2:17]
	s_setprio 0
	v_add_f32_e32 v0, v155, v106
	v_add_f32_e32 v0, v107, v0
	v_add_f32_e32 v0, v108, v0
	v_add_f32_e32 v0, v109, v0
	v_add_f32_e32 v0, v110, v0
	v_add_f32_e32 v0, v111, v0
	v_add_f32_e32 v0, v112, v0
	v_add_f32_e32 v0, v113, v0
	v_add_f32_e32 v0, v114, v0
	v_add_f32_e32 v0, v114, v0
	v_add_f32_e32 v0, v114, v0
	v_add_f32_e32 v0, v114, v0
	v_add_f32_e32 v0, v114, v0
	v_add_f32_e32 v0, v114, v0
	v_add_f32_e32 v0, v114, v0
	v_add_f32_e32 v0, v114, v0
	ds_bpermute_b32 v66, v149, v0
	s_waitcnt vmcnt(0)
	s_barrier
	s_waitcnt lgkmcnt(0)
	v_add_f32_e32 v66, v0, v66
	v_div_scale_f32 v67, s[0:1], v66, v66, 1.0
	v_rcp_f32_e32 v68, v67
	v_div_scale_f32 v69, vcc, 1.0, v66, 1.0
	v_lshlrev_b32_e32 v0, 4, v147
	v_fma_f32 v70, -v67, v68, 1.0
	v_fmac_f32_e32 v68, v70, v68
	v_mul_f32_e32 v70, v69, v68
	v_fma_f32 v71, -v67, v70, v69
	v_fmac_f32_e32 v70, v71, v68
	v_fma_f32 v67, -v67, v70, v69
	v_div_fmas_f32 v67, v67, v68, v70
	v_div_fixup_f32 v66, v67, v66, 1.0
	v_lshl_add_u64 v[68:69], v[150:151], 0, v[0:1]
	v_pk_mul_f32 v[50:51], v[50:51], v[66:67] op_sel_hi:[1,0]
	v_pk_mul_f32 v[52:53], v[52:53], v[66:67] op_sel_hi:[1,0]
	v_pk_mul_f32 v[54:55], v[54:55], v[66:67] op_sel_hi:[1,0]
	v_pk_mul_f32 v[56:57], v[56:57], v[66:67] op_sel_hi:[1,0]
	v_pk_mul_f32 v[58:59], v[58:59], v[66:67] op_sel_hi:[1,0]
	v_pk_mul_f32 v[60:61], v[60:61], v[66:67] op_sel_hi:[1,0]
	v_pk_mul_f32 v[62:63], v[62:63], v[66:67] op_sel_hi:[1,0]
	v_pk_mul_f32 v[64:65], v[64:65], v[66:67] op_sel_hi:[1,0]
	v_cvt_pk_bf16_f32 v50, v50, v51
	v_cvt_pk_bf16_f32 v51, v52, v53
	v_cvt_pk_bf16_f32 v52, v54, v55
	v_cvt_pk_bf16_f32 v53, v56, v57
	v_cvt_pk_bf16_f32 v54, v58, v59
	v_cvt_pk_bf16_f32 v55, v60, v61
	v_cvt_pk_bf16_f32 v56, v62, v63
	v_cvt_pk_bf16_f32 v57, v64, v65
	s_nop 1
	v_permlane32_swap_b32_e32 v50, v52
	v_permlane32_swap_b32_e32 v51, v53
	v_permlane32_swap_b32_e32 v54, v56
	v_permlane32_swap_b32_e32 v55, v57
	global_store_dwordx4 v[68:69], v[50:53], off
	global_store_dwordx4 v[68:69], v[54:57], off offset:32
	v_pk_mul_f32 v[34:35], v[34:35], v[66:67] op_sel_hi:[1,0]
	v_pk_mul_f32 v[36:37], v[36:37], v[66:67] op_sel_hi:[1,0]
	v_pk_mul_f32 v[38:39], v[38:39], v[66:67] op_sel_hi:[1,0]
	v_pk_mul_f32 v[40:41], v[40:41], v[66:67] op_sel_hi:[1,0]
	v_pk_mul_f32 v[42:43], v[42:43], v[66:67] op_sel_hi:[1,0]
	v_pk_mul_f32 v[44:45], v[44:45], v[66:67] op_sel_hi:[1,0]
	v_pk_mul_f32 v[46:47], v[46:47], v[66:67] op_sel_hi:[1,0]
	v_pk_mul_f32 v[48:49], v[48:49], v[66:67] op_sel_hi:[1,0]
	v_cvt_pk_bf16_f32 v34, v34, v35
	v_cvt_pk_bf16_f32 v35, v36, v37
	v_cvt_pk_bf16_f32 v36, v38, v39
	v_cvt_pk_bf16_f32 v37, v40, v41
	v_cvt_pk_bf16_f32 v38, v42, v43
	v_cvt_pk_bf16_f32 v39, v44, v45
	v_cvt_pk_bf16_f32 v40, v46, v47
	v_cvt_pk_bf16_f32 v41, v48, v49
	s_nop 1
	v_permlane32_swap_b32_e32 v34, v36
	v_permlane32_swap_b32_e32 v35, v37
	v_permlane32_swap_b32_e32 v38, v40
	v_permlane32_swap_b32_e32 v39, v41
	global_store_dwordx4 v[68:69], v[34:37], off offset:64
	global_store_dwordx4 v[68:69], v[38:41], off offset:96
	v_pk_mul_f32 v[18:19], v[18:19], v[66:67] op_sel_hi:[1,0]
	v_pk_mul_f32 v[20:21], v[20:21], v[66:67] op_sel_hi:[1,0]
	v_pk_mul_f32 v[22:23], v[22:23], v[66:67] op_sel_hi:[1,0]
	v_pk_mul_f32 v[24:25], v[24:25], v[66:67] op_sel_hi:[1,0]
	v_pk_mul_f32 v[26:27], v[26:27], v[66:67] op_sel_hi:[1,0]
	v_pk_mul_f32 v[28:29], v[28:29], v[66:67] op_sel_hi:[1,0]
	v_pk_mul_f32 v[30:31], v[30:31], v[66:67] op_sel_hi:[1,0]
	v_pk_mul_f32 v[32:33], v[32:33], v[66:67] op_sel_hi:[1,0]
	v_cvt_pk_bf16_f32 v18, v18, v19
	v_cvt_pk_bf16_f32 v19, v20, v21
	v_cvt_pk_bf16_f32 v20, v22, v23
	v_cvt_pk_bf16_f32 v21, v24, v25
	v_cvt_pk_bf16_f32 v22, v26, v27
	v_cvt_pk_bf16_f32 v23, v28, v29
	v_cvt_pk_bf16_f32 v24, v30, v31
	v_cvt_pk_bf16_f32 v25, v32, v33
	s_nop 1
	v_permlane32_swap_b32_e32 v18, v20
	v_permlane32_swap_b32_e32 v19, v21
	v_permlane32_swap_b32_e32 v22, v24
	v_permlane32_swap_b32_e32 v23, v25
	global_store_dwordx4 v[68:69], v[18:21], off offset:128
	global_store_dwordx4 v[68:69], v[22:25], off offset:160
	v_pk_mul_f32 v[2:3], v[2:3], v[66:67] op_sel_hi:[1,0]
	v_pk_mul_f32 v[4:5], v[4:5], v[66:67] op_sel_hi:[1,0]
	v_pk_mul_f32 v[6:7], v[6:7], v[66:67] op_sel_hi:[1,0]
	v_pk_mul_f32 v[8:9], v[8:9], v[66:67] op_sel_hi:[1,0]
	v_pk_mul_f32 v[10:11], v[10:11], v[66:67] op_sel_hi:[1,0]
	v_pk_mul_f32 v[12:13], v[12:13], v[66:67] op_sel_hi:[1,0]
	v_pk_mul_f32 v[14:15], v[14:15], v[66:67] op_sel_hi:[1,0]
	v_pk_mul_f32 v[16:17], v[16:17], v[66:67] op_sel_hi:[1,0]
	v_cvt_pk_bf16_f32 v2, v2, v3
	v_cvt_pk_bf16_f32 v3, v4, v5
	v_cvt_pk_bf16_f32 v4, v6, v7
	v_cvt_pk_bf16_f32 v5, v8, v9
	v_cvt_pk_bf16_f32 v6, v10, v11
	v_cvt_pk_bf16_f32 v7, v12, v13
	v_cvt_pk_bf16_f32 v8, v14, v15
	v_cvt_pk_bf16_f32 v9, v16, v17
	s_nop 1
	v_permlane32_swap_b32_e32 v2, v4
	v_permlane32_swap_b32_e32 v3, v5
	v_permlane32_swap_b32_e32 v6, v8
	v_permlane32_swap_b32_e32 v7, v9
	global_store_dwordx4 v[68:69], v[2:5], off offset:192
	global_store_dwordx4 v[68:69], v[6:9], off offset:224
	s_waitcnt vmcnt(0)
	s_barrier
